# v22 + down-proj epilogue: half of the second-half residual (XN) loads issued together with the first half's loads
# baseline (speedup 1.0000x reference)
; #define PG8_LAS __attribute__((address_space(3)))
;     __device__ __forceinline__ void operator()(Acc& acc, const Unit& u, int wr, int wc, int fr, int fq, PG8_LAS unsigned char*, const Pre& P) const {
;         const int col0 = u.pn * 256 + wc * 32 + 4 * fq;
; #pragma unroll
;         for (int ai = 0; ai < 2; ++ai) {
;             u32x2 xv[4][2][2];
; #pragma unroll
;             for (int m = 0; m < 4; ++m) { const int row = u.pm * 256 + ai * 128 + wr * 64 + m * 16 + fr;
; #pragma unroll
;                 for (int bj = 0; bj < 2; ++bj)
; #pragma unroll
;                     for (int n = 0; n < 2; ++n) xv[m][bj][n] = *(const u32x2*)(src + (size_t)((u.pm * 256) >> 12) * (SEQ * (INC - DM)) + (size_t)row * DM + col0 + bj * 128 + n * 16); }
; #pragma unroll
;             for (int m = 0; m < 4; ++m) {
;                 const int row = u.pm * 256 + ai * 128 + wr * 64 + m * 16 + fr;
; #pragma unroll
;                 for (int bj = 0; bj < 2; ++bj)
; #pragma unroll
;                     for (int n = 0; n < 2; ++n) { const u32x2 w = xv[m][bj][n]; const f32x4 xf = {__uint_as_float(w.x << 16), __uint_as_float(w.x & 0xffff0000u), __uint_as_float(w.y << 16), __uint_as_float(w.y & 0xffff0000u)};
;                         *(f32x4*)(out + (size_t)row * DM + col0 + bj * 128 + n * 16) = xf + P.gv[bj][n] * acc[ai][bj][m][n]; }
;             }
;             asm volatile("" ::: "memory");
;         }
;     }
.LBB0_1051:
	s_ashr_i32 s18, s49, 4
	s_mul_hi_i32 s19, s18, 0xa00000
	s_mul_i32 s18, s18, 0xa00000
	v_lshl_add_u32 v158, s50, 8, v168
	v_lshl_add_u32 v160, s49, 8, v166
	s_add_u32 s18, s41, s18
	v_ashrrev_i32_e32 v159, 31, v158
	s_addc_u32 s19, s42, s19
	v_ashrrev_i32_e32 v161, 31, v160
	v_lshl_add_u64 v[162:163], v[158:159], 1, s[18:19]
	v_lshlrev_b64 v[164:165], 11, v[160:161]
	v_lshl_add_u64 v[164:165], v[162:163], 0, v[164:165]
	v_or_b32_e32 v178, 16, v160
	global_load_dwordx2 v[172:173], v[164:165], off
	global_load_dwordx2 v[174:175], v[164:165], off offset:32
	global_load_dwordx2 v[176:177], v[164:165], off offset:256
	global_load_dwordx2 v[180:181], v[164:165], off offset:288
	v_ashrrev_i32_e32 v179, 31, v178
	v_lshlrev_b64 v[164:165], 11, v[178:179]
	v_lshl_add_u64 v[164:165], v[162:163], 0, v[164:165]
	v_or_b32_e32 v190, 32, v160
	global_load_dwordx2 v[182:183], v[164:165], off
	global_load_dwordx2 v[184:185], v[164:165], off offset:32
	global_load_dwordx2 v[186:187], v[164:165], off offset:256
	global_load_dwordx2 v[188:189], v[164:165], off offset:288
	v_ashrrev_i32_e32 v191, 31, v190
	v_lshlrev_b64 v[164:165], 11, v[190:191]
	v_lshl_add_u64 v[192:193], v[162:163], 0, v[164:165]
	global_load_dwordx2 v[194:195], v[192:193], off
	global_load_dwordx2 v[198:199], v[192:193], off offset:32
	global_load_dwordx2 v[202:203], v[192:193], off offset:256
	v_or_b32_e32 v164, 48, v160
	v_ashrrev_i32_e32 v165, 31, v164
	v_lshlrev_b64 v[200:201], 11, v[164:165]
	v_lshl_add_u64 v[200:201], v[162:163], 0, v[200:201]
	global_load_dwordx2 v[192:193], v[192:193], off offset:288
	s_nop 0
	global_load_dwordx2 v[204:205], v[200:201], off
	global_load_dwordx2 v[206:207], v[200:201], off offset:32
	global_load_dwordx2 v[208:209], v[200:201], off offset:256
	s_nop 0
	global_load_dwordx2 v[200:201], v[200:201], off offset:288
	v_add_u32_e32 v254, 0x80, v160
	v_lshlrev_b32_e32 v254, 11, v254
	v_add_co_u32_e32 v252, vcc, v162, v254
	v_addc_co_u32_e32 v253, vcc, 0, v163, vcc
	global_load_dwordx2 v[238:239], v[252:253], off
	global_load_dwordx2 v[240:241], v[252:253], off offset:32
	global_load_dwordx2 v[242:243], v[252:253], off offset:256
	global_load_dwordx2 v[244:245], v[252:253], off offset:288
	v_add_u32_e32 v254, 0x90, v160
	v_lshlrev_b32_e32 v254, 11, v254
	v_add_co_u32_e32 v252, vcc, v162, v254
	v_addc_co_u32_e32 v253, vcc, 0, v163, vcc
	global_load_dwordx2 v[246:247], v[252:253], off
	global_load_dwordx2 v[248:249], v[252:253], off offset:32
	global_load_dwordx2 v[250:251], v[252:253], off offset:256
	s_nop 0
	global_load_dwordx2 v[252:253], v[252:253], off offset:288
	v_lshlrev_b64 v[196:197], 12, v[160:161]
	v_lshlrev_b64 v[158:159], 2, v[158:159]
	v_lshl_add_u64 v[196:197], s[6:7], 0, v[196:197]
	v_lshlrev_b64 v[178:179], 12, v[178:179]
	v_lshl_add_u64 v[196:197], v[196:197], 0, v[158:159]
	v_lshl_add_u64 v[178:179], s[6:7], 0, v[178:179]
	v_lshl_add_u64 v[178:179], v[178:179], 0, v[158:159]
	s_and_b64 vcc, exec, s[0:1]
	s_mov_b64 s[0:1], -1
	s_waitcnt vmcnt(8)
	v_lshlrev_b32_e32 v210, 16, v172
	v_and_b32_e32 v211, 0xffff0000, v172
	v_lshlrev_b32_e32 v172, 16, v173
	v_and_b32_e32 v173, 0xffff0000, v173
	v_lshlrev_b32_e32 v216, 16, v180
	v_and_b32_e32 v217, 0xffff0000, v180
	v_lshlrev_b32_e32 v180, 16, v181
	v_and_b32_e32 v181, 0xffff0000, v181
	v_lshlrev_b32_e32 v212, 16, v174
	v_and_b32_e32 v213, 0xffff0000, v174
	v_lshlrev_b32_e32 v174, 16, v175
	v_and_b32_e32 v175, 0xffff0000, v175
	v_lshlrev_b32_e32 v214, 16, v176
	v_and_b32_e32 v215, 0xffff0000, v176
	v_lshlrev_b32_e32 v176, 16, v177
	v_and_b32_e32 v177, 0xffff0000, v177
	v_lshlrev_b32_e32 v218, 16, v182
	v_and_b32_e32 v219, 0xffff0000, v182
	v_lshlrev_b32_e32 v182, 16, v183
	v_and_b32_e32 v183, 0xffff0000, v183
	v_lshlrev_b32_e32 v220, 16, v184
	v_and_b32_e32 v221, 0xffff0000, v184
	v_lshlrev_b32_e32 v184, 16, v185
	v_and_b32_e32 v185, 0xffff0000, v185
	v_pk_fma_f32 v[142:143], v[14:15], v[142:143], v[172:173]
	v_pk_fma_f32 v[140:141], v[12:13], v[140:141], v[210:211]
	v_pk_fma_f32 v[122:123], v[2:3], v[122:123], v[180:181]
	v_pk_fma_f32 v[120:121], v[0:1], v[120:121], v[216:217]
	v_pk_fma_f32 v[138:139], v[10:11], v[138:139], v[174:175]
	v_pk_fma_f32 v[136:137], v[8:9], v[136:137], v[212:213]
	v_pk_fma_f32 v[126:127], v[6:7], v[126:127], v[176:177]
	v_pk_fma_f32 v[124:125], v[4:5], v[124:125], v[214:215]
	v_pk_fma_f32 v[134:135], v[14:15], v[134:135], v[182:183]
	v_pk_fma_f32 v[132:133], v[12:13], v[132:133], v[218:219]
	v_pk_fma_f32 v[130:131], v[10:11], v[130:131], v[184:185]
	v_pk_fma_f32 v[128:129], v[8:9], v[128:129], v[220:221]
	global_store_dwordx4 v[196:197], v[140:143], off
	global_store_dwordx4 v[196:197], v[136:139], off offset:64
	global_store_dwordx4 v[196:197], v[124:127], off offset:512
	global_store_dwordx4 v[196:197], v[120:123], off offset:576
	global_store_dwordx4 v[178:179], v[132:135], off
	global_store_dwordx4 v[178:179], v[128:131], off offset:64
	v_lshlrev_b32_e32 v120, 16, v186
	v_and_b32_e32 v121, 0xffff0000, v186
	v_lshlrev_b32_e32 v122, 16, v187
	v_and_b32_e32 v123, 0xffff0000, v187
	v_pk_fma_f32 v[118:119], v[6:7], v[118:119], v[122:123]
	v_pk_fma_f32 v[116:117], v[4:5], v[116:117], v[120:121]
	global_store_dwordx4 v[178:179], v[116:119], off offset:512
	s_nop 1
	v_lshlrev_b32_e32 v116, 16, v188
	v_and_b32_e32 v117, 0xffff0000, v188
	v_lshlrev_b32_e32 v118, 16, v189
	v_and_b32_e32 v119, 0xffff0000, v189
	v_pk_fma_f32 v[110:111], v[2:3], v[110:111], v[118:119]
	v_pk_fma_f32 v[108:109], v[0:1], v[108:109], v[116:117]
	global_store_dwordx4 v[178:179], v[108:111], off offset:576
	v_lshlrev_b64 v[116:117], 12, v[190:191]
	s_nop 0
	v_lshlrev_b32_e32 v108, 16, v194
; #define PG8_LAS __attribute__((address_space(3)))
;     __device__ __forceinline__ void operator()(Acc& acc, const Unit& u, int wr, int wc, int fr, int fq, PG8_LAS unsigned char*, const Pre& P) const {
;         const int col0 = u.pn * 256 + wc * 32 + 4 * fq;
; #pragma unroll
;         for (int ai = 0; ai < 2; ++ai) {
;             u32x2 xv[4][2][2];
; #pragma unroll
;             for (int m = 0; m < 4; ++m) { const int row = u.pm * 256 + ai * 128 + wr * 64 + m * 16 + fr;
; #pragma unroll
;                 for (int bj = 0; bj < 2; ++bj)
; #pragma unroll
;                     for (int n = 0; n < 2; ++n) xv[m][bj][n] = *(const u32x2*)(src + (size_t)((u.pm * 256) >> 12) * (SEQ * (INC - DM)) + (size_t)row * DM + col0 + bj * 128 + n * 16); }
; #pragma unroll
;             for (int m = 0; m < 4; ++m) {
;                 const int row = u.pm * 256 + ai * 128 + wr * 64 + m * 16 + fr;
; #pragma unroll
;                 for (int bj = 0; bj < 2; ++bj)
; #pragma unroll
;                     for (int n = 0; n < 2; ++n) { const u32x2 w = xv[m][bj][n]; const f32x4 xf = {__uint_as_float(w.x << 16), __uint_as_float(w.x & 0xffff0000u), __uint_as_float(w.y << 16), __uint_as_float(w.y & 0xffff0000u)};
;                         *(f32x4*)(out + (size_t)row * DM + col0 + bj * 128 + n * 16) = xf + P.gv[bj][n] * acc[ai][bj][m][n]; }
;             }
;             asm volatile("" ::: "memory");
;         }
;     }
	v_and_b32_e32 v109, 0xffff0000, v194
	v_lshlrev_b32_e32 v110, 16, v195
	v_and_b32_e32 v111, 0xffff0000, v195
	v_pk_fma_f32 v[108:109], v[12:13], v[112:113], v[108:109]
	v_lshl_add_u64 v[112:113], s[6:7], 0, v[116:117]
	v_pk_fma_f32 v[110:111], v[14:15], v[114:115], v[110:111]
	v_lshl_add_u64 v[112:113], v[112:113], 0, v[158:159]
	global_store_dwordx4 v[112:113], v[108:111], off
	v_add_u32_e32 v114, 0xb0, v160
	v_ashrrev_i32_e32 v115, 31, v114
	v_lshlrev_b32_e32 v108, 16, v198
	v_and_b32_e32 v109, 0xffff0000, v198
	v_lshlrev_b32_e32 v110, 16, v199
	v_and_b32_e32 v111, 0xffff0000, v199
	v_pk_fma_f32 v[106:107], v[10:11], v[106:107], v[110:111]
	v_pk_fma_f32 v[104:105], v[8:9], v[104:105], v[108:109]
	global_store_dwordx4 v[112:113], v[104:107], off offset:64
	s_nop 1
	v_lshlrev_b32_e32 v104, 16, v202
	v_and_b32_e32 v105, 0xffff0000, v202
	v_lshlrev_b32_e32 v106, 16, v203
	v_and_b32_e32 v107, 0xffff0000, v203
	v_pk_fma_f32 v[102:103], v[6:7], v[102:103], v[106:107]
	v_pk_fma_f32 v[100:101], v[4:5], v[100:101], v[104:105]
	global_store_dwordx4 v[112:113], v[100:103], off offset:512
	v_add_u32_e32 v104, 0xa0, v160
	v_ashrrev_i32_e32 v105, 31, v104
	v_lshlrev_b32_e32 v100, 16, v192
	v_and_b32_e32 v101, 0xffff0000, v192
	v_lshlrev_b32_e32 v102, 16, v193
	v_and_b32_e32 v103, 0xffff0000, v193
	v_pk_fma_f32 v[94:95], v[2:3], v[94:95], v[102:103]
	v_pk_fma_f32 v[92:93], v[0:1], v[92:93], v[100:101]
	global_store_dwordx4 v[112:113], v[92:95], off offset:576
	v_lshlrev_b64 v[100:101], 12, v[164:165]
	s_nop 0
	v_lshlrev_b32_e32 v92, 16, v204
	v_and_b32_e32 v93, 0xffff0000, v204
	v_lshlrev_b32_e32 v94, 16, v205
	v_and_b32_e32 v95, 0xffff0000, v205
	v_pk_fma_f32 v[92:93], v[12:13], v[96:97], v[92:93]
	v_lshl_add_u64 v[96:97], s[6:7], 0, v[100:101]
	v_pk_fma_f32 v[94:95], v[14:15], v[98:99], v[94:95]
	v_lshl_add_u64 v[96:97], v[96:97], 0, v[158:159]
	global_store_dwordx4 v[96:97], v[92:95], off
	s_nop 1
	v_lshlrev_b32_e32 v92, 16, v206
	v_and_b32_e32 v93, 0xffff0000, v206
	v_lshlrev_b32_e32 v94, 16, v207
	v_and_b32_e32 v95, 0xffff0000, v207
	v_pk_fma_f32 v[90:91], v[10:11], v[90:91], v[94:95]
	v_pk_fma_f32 v[88:89], v[8:9], v[88:89], v[92:93]
	global_store_dwordx4 v[96:97], v[88:91], off offset:64
	v_add_u32_e32 v94, 0x90, v160
	v_ashrrev_i32_e32 v95, 31, v94
	v_lshlrev_b32_e32 v88, 16, v208
	v_and_b32_e32 v89, 0xffff0000, v208
	v_lshlrev_b32_e32 v90, 16, v209
	v_and_b32_e32 v91, 0xffff0000, v209
	v_pk_fma_f32 v[86:87], v[6:7], v[86:87], v[90:91]
	v_pk_fma_f32 v[84:85], v[4:5], v[84:85], v[88:89]
	global_store_dwordx4 v[96:97], v[84:87], off offset:512
	s_nop 1
	v_lshlrev_b32_e32 v84, 16, v200
	v_and_b32_e32 v85, 0xffff0000, v200
	v_lshlrev_b32_e32 v86, 16, v201
	v_and_b32_e32 v87, 0xffff0000, v201
	v_pk_fma_f32 v[80:81], v[0:1], v[80:81], v[84:85]
	v_add_u32_e32 v84, 0x80, v160
	v_pk_fma_f32 v[82:83], v[2:3], v[82:83], v[86:87]
	v_ashrrev_i32_e32 v85, 31, v84
	global_store_dwordx4 v[96:97], v[80:83], off offset:576
	s_nop 1
	v_lshlrev_b64 v[80:81], 11, v[104:105]
	v_lshl_add_u64 v[80:81], v[162:163], 0, v[80:81]
	global_load_dwordx2 v[106:107], v[80:81], off
	global_load_dwordx2 v[108:109], v[80:81], off offset:32
	global_load_dwordx2 v[110:111], v[80:81], off offset:256
	global_load_dwordx2 v[112:113], v[80:81], off offset:288
	v_lshlrev_b64 v[80:81], 11, v[114:115]
	v_lshl_add_u64 v[80:81], v[162:163], 0, v[80:81]
	global_load_dwordx2 v[116:117], v[80:81], off
	global_load_dwordx2 v[118:119], v[80:81], off offset:32
	global_load_dwordx2 v[82:83], v[80:81], off offset:256
	s_nop 0
	global_load_dwordx2 v[80:81], v[80:81], off offset:288
	v_lshlrev_b64 v[84:85], 12, v[84:85]
	v_lshl_add_u64 v[84:85], s[6:7], 0, v[84:85]
	v_lshl_add_u64 v[84:85], v[84:85], 0, v[158:159]
	s_waitcnt vmcnt(31)
	v_lshlrev_b32_e32 v120, 16, v238
	v_and_b32_e32 v121, 0xffff0000, v238
	v_lshlrev_b32_e32 v238, 16, v239
	v_and_b32_e32 v239, 0xffff0000, v239
	v_pk_fma_f32 v[78:79], v[14:15], v[78:79], v[238:239]
	v_pk_fma_f32 v[76:77], v[12:13], v[76:77], v[120:121]
	global_store_dwordx4 v[84:85], v[76:79], off
	s_waitcnt vmcnt(31)
	s_nop 0
	v_lshlrev_b32_e32 v76, 16, v240
	v_and_b32_e32 v77, 0xffff0000, v240
	v_lshlrev_b32_e32 v78, 16, v241
	v_and_b32_e32 v79, 0xffff0000, v241
	v_pk_fma_f32 v[74:75], v[10:11], v[74:75], v[78:79]
	v_pk_fma_f32 v[72:73], v[8:9], v[72:73], v[76:77]
	global_store_dwordx4 v[84:85], v[72:75], off offset:64
	s_waitcnt vmcnt(31)
	s_nop 0
	v_lshlrev_b32_e32 v72, 16, v242
	v_and_b32_e32 v73, 0xffff0000, v242
	v_lshlrev_b32_e32 v74, 16, v243
	v_and_b32_e32 v75, 0xffff0000, v243
	v_pk_fma_f32 v[70:71], v[6:7], v[70:71], v[74:75]
	v_pk_fma_f32 v[68:69], v[4:5], v[68:69], v[72:73]
	global_store_dwordx4 v[84:85], v[68:71], off offset:512
	s_waitcnt vmcnt(31)
	s_nop 0
	v_lshlrev_b32_e32 v68, 16, v244
	v_and_b32_e32 v69, 0xffff0000, v244
	v_lshlrev_b32_e32 v70, 16, v245
	v_and_b32_e32 v71, 0xffff0000, v245
	v_pk_fma_f32 v[62:63], v[2:3], v[62:63], v[70:71]
	v_pk_fma_f32 v[60:61], v[0:1], v[60:61], v[68:69]
	global_store_dwordx4 v[84:85], v[60:63], off offset:576
	v_lshlrev_b64 v[68:69], 12, v[94:95]
	s_waitcnt vmcnt(31)
; #define PG8_LAS __attribute__((address_space(3)))
;     __device__ __forceinline__ void prefetch(Pre& P, const Unit& u, int wr, int wc, int fr, int fq) const {
;         const float* g2p = mod + (size_t)((u.pm * 256) >> 12) * NMOD + 5 * DM + u.pn * 256 + wc * 32 + 4 * fq;
; #pragma unroll
;         for (int bj = 0; bj < 2; ++bj)
; #pragma unroll
;             for (int n = 0; n < 2; ++n) P.gv[bj][n] = *(const f32x4*)(g2p + bj * 128 + n * 16);
;     }
;     __device__ __forceinline__ void operator()(Acc& acc, const Unit& u, int wr, int wc, int fr, int fq, PG8_LAS unsigned char*, const Pre& P) const {
;         const int col0 = u.pn * 256 + wc * 32 + 4 * fq;
; #pragma unroll
;         for (int ai = 0; ai < 2; ++ai) {
;             u32x2 xv[4][2][2];
; #pragma unroll
;             for (int m = 0; m < 4; ++m) { const int row = u.pm * 256 + ai * 128 + wr * 64 + m * 16 + fr;
; #pragma unroll
;                 for (int bj = 0; bj < 2; ++bj)
; #pragma unroll
;                     for (int n = 0; n < 2; ++n) xv[m][bj][n] = *(const u32x2*)(src + (size_t)((u.pm * 256) >> 12) * (SEQ * (INC - DM)) + (size_t)row * DM + col0 + bj * 128 + n * 16); }
; #pragma unroll
;             for (int m = 0; m < 4; ++m) {
;                 const int row = u.pm * 256 + ai * 128 + wr * 64 + m * 16 + fr;
; #pragma unroll
;                 for (int bj = 0; bj < 2; ++bj)
; #pragma unroll
;                     for (int n = 0; n < 2; ++n) { const u32x2 w = xv[m][bj][n]; const f32x4 xf = {__uint_as_float(w.x << 16), __uint_as_float(w.x & 0xffff0000u), __uint_as_float(w.y << 16), __uint_as_float(w.y & 0xffff0000u)};
;                         *(f32x4*)(out + (size_t)row * DM + col0 + bj * 128 + n * 16) = xf + P.gv[bj][n] * acc[ai][bj][m][n]; }
;             }
;             asm volatile("" ::: "memory");
;         }
;     }
	v_lshlrev_b32_e32 v60, 16, v246
	v_and_b32_e32 v61, 0xffff0000, v246
	v_lshlrev_b32_e32 v62, 16, v247
	v_and_b32_e32 v63, 0xffff0000, v247
	v_pk_fma_f32 v[60:61], v[12:13], v[64:65], v[60:61]
	v_lshl_add_u64 v[64:65], s[6:7], 0, v[68:69]
	v_pk_fma_f32 v[62:63], v[14:15], v[66:67], v[62:63]
	v_lshl_add_u64 v[64:65], v[64:65], 0, v[158:159]
	global_store_dwordx4 v[64:65], v[60:63], off
	s_waitcnt vmcnt(31)
	s_nop 0
	v_lshlrev_b32_e32 v60, 16, v248
	v_and_b32_e32 v61, 0xffff0000, v248
	v_lshlrev_b32_e32 v62, 16, v249
	v_and_b32_e32 v63, 0xffff0000, v249
	v_pk_fma_f32 v[58:59], v[10:11], v[58:59], v[62:63]
	v_pk_fma_f32 v[56:57], v[8:9], v[56:57], v[60:61]
	global_store_dwordx4 v[64:65], v[56:59], off offset:64
	s_waitcnt vmcnt(31)
	s_nop 0
	v_lshlrev_b32_e32 v56, 16, v250
	v_and_b32_e32 v57, 0xffff0000, v250
	v_lshlrev_b32_e32 v58, 16, v251
	v_and_b32_e32 v59, 0xffff0000, v251
	v_pk_fma_f32 v[54:55], v[6:7], v[54:55], v[58:59]
	v_pk_fma_f32 v[52:53], v[4:5], v[52:53], v[56:57]
	global_store_dwordx4 v[64:65], v[52:55], off offset:512
	s_waitcnt vmcnt(31)
	s_nop 0
	v_lshlrev_b32_e32 v52, 16, v252
	v_and_b32_e32 v53, 0xffff0000, v252
	v_lshlrev_b32_e32 v54, 16, v253
	v_and_b32_e32 v55, 0xffff0000, v253
	v_pk_fma_f32 v[46:47], v[2:3], v[46:47], v[54:55]
	v_pk_fma_f32 v[44:45], v[0:1], v[44:45], v[52:53]
	global_store_dwordx4 v[64:65], v[44:47], off offset:576
	v_lshlrev_b64 v[52:53], 12, v[104:105]
	s_waitcnt vmcnt(15)
	v_lshlrev_b32_e32 v44, 16, v106
	v_and_b32_e32 v45, 0xffff0000, v106
	v_lshlrev_b32_e32 v46, 16, v107
	v_and_b32_e32 v47, 0xffff0000, v107
	v_pk_fma_f32 v[44:45], v[12:13], v[48:49], v[44:45]
	v_lshl_add_u64 v[48:49], s[6:7], 0, v[52:53]
	v_pk_fma_f32 v[46:47], v[14:15], v[50:51], v[46:47]
	v_lshl_add_u64 v[48:49], v[48:49], 0, v[158:159]
	global_store_dwordx4 v[48:49], v[44:47], off
	s_waitcnt vmcnt(15)
	s_nop 0
	v_lshlrev_b32_e32 v44, 16, v108
	v_and_b32_e32 v45, 0xffff0000, v108
	v_lshlrev_b32_e32 v46, 16, v109
	v_and_b32_e32 v47, 0xffff0000, v109
	v_pk_fma_f32 v[42:43], v[10:11], v[42:43], v[46:47]
	v_pk_fma_f32 v[40:41], v[8:9], v[40:41], v[44:45]
	global_store_dwordx4 v[48:49], v[40:43], off offset:64
	s_waitcnt vmcnt(15)
	s_nop 0
	v_lshlrev_b32_e32 v40, 16, v110
	v_and_b32_e32 v41, 0xffff0000, v110
	v_lshlrev_b32_e32 v42, 16, v111
	v_and_b32_e32 v43, 0xffff0000, v111
	v_pk_fma_f32 v[38:39], v[6:7], v[38:39], v[42:43]
	v_pk_fma_f32 v[36:37], v[4:5], v[36:37], v[40:41]
	global_store_dwordx4 v[48:49], v[36:39], off offset:512
	s_waitcnt vmcnt(15)
	s_nop 0
	v_lshlrev_b32_e32 v36, 16, v112
	v_and_b32_e32 v37, 0xffff0000, v112
	v_lshlrev_b32_e32 v38, 16, v113
	v_and_b32_e32 v39, 0xffff0000, v113
	v_pk_fma_f32 v[30:31], v[2:3], v[30:31], v[38:39]
	v_pk_fma_f32 v[28:29], v[0:1], v[28:29], v[36:37]
	global_store_dwordx4 v[48:49], v[28:31], off offset:576
	s_waitcnt vmcnt(15)
	v_lshlrev_b32_e32 v36, 16, v117
	v_and_b32_e32 v37, 0xffff0000, v117
	v_lshlrev_b64 v[28:29], 12, v[114:115]
	v_lshlrev_b32_e32 v30, 16, v116
	v_and_b32_e32 v31, 0xffff0000, v116
	v_lshl_add_u64 v[28:29], s[6:7], 0, v[28:29]
	v_pk_fma_f32 v[14:15], v[14:15], v[34:35], v[36:37]
	v_pk_fma_f32 v[12:13], v[12:13], v[32:33], v[30:31]
	v_lshl_add_u64 v[28:29], v[28:29], 0, v[158:159]
	global_store_dwordx4 v[28:29], v[12:15], off
	s_waitcnt vmcnt(15)
	s_nop 0
	v_lshlrev_b32_e32 v12, 16, v118
	v_and_b32_e32 v13, 0xffff0000, v118
	v_lshlrev_b32_e32 v14, 16, v119
	v_and_b32_e32 v15, 0xffff0000, v119
	v_pk_fma_f32 v[10:11], v[10:11], v[26:27], v[14:15]
	v_pk_fma_f32 v[8:9], v[8:9], v[24:25], v[12:13]
	global_store_dwordx4 v[28:29], v[8:11], off offset:64
	s_waitcnt vmcnt(15)
	s_nop 0
	v_lshlrev_b32_e32 v8, 16, v82
	v_and_b32_e32 v9, 0xffff0000, v82
	v_lshlrev_b32_e32 v10, 16, v83
	v_and_b32_e32 v11, 0xffff0000, v83
	v_pk_fma_f32 v[6:7], v[6:7], v[22:23], v[10:11]
	v_pk_fma_f32 v[4:5], v[4:5], v[20:21], v[8:9]
	global_store_dwordx4 v[28:29], v[4:7], off offset:512
	s_waitcnt vmcnt(15)
	s_nop 0
	v_lshlrev_b32_e32 v4, 16, v80
	v_and_b32_e32 v5, 0xffff0000, v80
	v_lshlrev_b32_e32 v6, 16, v81
	v_and_b32_e32 v7, 0xffff0000, v81
	v_pk_fma_f32 v[2:3], v[2:3], v[18:19], v[6:7]
	v_pk_fma_f32 v[0:1], v[0:1], v[16:17], v[4:5]
	global_store_dwordx4 v[28:29], v[0:3], off offset:576
	s_cbranch_vccnz .LBB0_1036
	s_ashr_i32 s0, s48, 4
	s_mul_hi_i32 s1, s0, 0x6000
	s_mulk_i32 s0, 0x6000
	s_add_u32 s18, s4, s0
	s_addc_u32 s19, s5, s1
	s_lshl_b32 s0, s47, 8
	s_ashr_i32 s1, s0, 31
	s_lshl_b64 s[0:1], s[0:1], 2
	s_add_u32 s0, s18, s0
	s_addc_u32 s1, s19, s1
	s_add_u32 s0, s0, s34
	s_addc_u32 s1, s1, 0
	v_lshl_add_u64 v[0:1], v[148:149], 2, s[0:1]
	v_lshl_add_u64 v[16:17], v[0:1], 0, s[10:11]
	v_add_co_u32_e32 v18, vcc, 0x5000, v0
	s_nop 1
	v_addc_co_u32_e32 v19, vcc, 0, v1, vcc
	global_load_dwordx4 v[8:11], v[16:17], off offset:64
	global_load_dwordx4 v[4:7], v[16:17], off offset:512
	global_load_dwordx4 v[12:15], v[18:19], off
	global_load_dwordx4 v[0:3], v[16:17], off offset:576
	s_andn2_b64 vcc, exec, s[8:9]
	s_cbranch_vccnz .LBB0_1035
	s_barrier
	s_branch .LBB0_1035
